# unit boundary: the three compiler vmcnt(0) drains inside the accumulator-zeroing blocks removed (store-data WAR needs only the ISA wait states); on top of v49
# speedup vs baseline: 1.0046x; 1.0040x over previous
.LBB0_299:
	s_mov_b32 s24, s25
	s_ashr_i32 s25, s25, 31
	s_mov_b32 s81, s28
	s_lshl_b64 s[28:29], s[24:25], 19
	s_add_u32 s28, s60, s28
	s_addc_u32 s29, s61, s29
	s_and_b64 s[30:31], s[26:27], exec
	s_mov_b32 s22, s23
	s_cselect_b32 s20, s29, s43
	s_cselect_b32 s25, s28, s42
	s_ashr_i32 s23, s23, 31
	s_lshl_b64 s[30:31], s[22:23], 19
	s_add_u32 s30, s68, s30
	s_addc_u32 s31, s69, s31
	s_and_b64 s[44:45], s[26:27], exec
	s_cselect_b32 s23, s31, s41
	s_cselect_b32 s82, s30, s40
	s_add_u32 s83, s40, 0x100
	s_addc_u32 s84, s41, 0
	s_add_u32 s40, s42, 0x40080
	v_mov_b32_e32 v0, 0
	s_addc_u32 s41, s43, 0
	s_mov_b32 s85, -2
	v_mov_b32_e32 v1, v0
	v_mov_b32_e32 v2, v0
	v_mov_b32_e32 v3, v0
	v_mov_b32_e32 v8, v0
	v_mov_b32_e32 v9, v0
	v_mov_b32_e32 v10, v0
	v_mov_b32_e32 v11, v0
	v_mov_b32_e32 v16, v0
	v_mov_b32_e32 v17, v0
	v_mov_b32_e32 v18, v0
	v_mov_b32_e32 v19, v0
	v_mov_b32_e32 v24, v0
	v_mov_b32_e32 v25, v0
	v_mov_b32_e32 v26, v0
	v_mov_b32_e32 v27, v0
	v_mov_b32_e32 v32, v0
	v_mov_b32_e32 v33, v0
	v_mov_b32_e32 v34, v0
	v_mov_b32_e32 v35, v0
	v_mov_b32_e32 v40, v0
	v_mov_b32_e32 v41, v0
	v_mov_b32_e32 v42, v0
	v_mov_b32_e32 v43, v0
	v_mov_b32_e32 v48, v0
	v_mov_b32_e32 v49, v0
	v_mov_b32_e32 v50, v0
	v_mov_b32_e32 v51, v0
	v_mov_b32_e32 v56, v0
	v_mov_b32_e32 v57, v0
	v_mov_b32_e32 v58, v0
	v_mov_b32_e32 v59, v0
	v_mov_b32_e32 v4, v0
	v_mov_b32_e32 v5, v0
	v_mov_b32_e32 v6, v0
	v_mov_b32_e32 v7, v0
	v_mov_b32_e32 v12, v0
	v_mov_b32_e32 v13, v0
	v_mov_b32_e32 v14, v0
	v_mov_b32_e32 v15, v0
	v_mov_b32_e32 v20, v0
	v_mov_b32_e32 v21, v0
	v_mov_b32_e32 v22, v0
	v_mov_b32_e32 v23, v0
	v_mov_b32_e32 v28, v0
	v_mov_b32_e32 v29, v0
	v_mov_b32_e32 v30, v0
	v_mov_b32_e32 v31, v0
	v_mov_b32_e32 v36, v0
	v_mov_b32_e32 v37, v0
	v_mov_b32_e32 v38, v0
	v_mov_b32_e32 v39, v0
	v_mov_b32_e32 v44, v0
	v_mov_b32_e32 v45, v0
	v_mov_b32_e32 v46, v0
	v_mov_b32_e32 v47, v0
	v_mov_b32_e32 v52, v0
	v_mov_b32_e32 v53, v0
	v_mov_b32_e32 v54, v0
	v_mov_b32_e32 v55, v0
	v_mov_b32_e32 v60, v0
	v_mov_b32_e32 v61, v0
	v_mov_b32_e32 v62, v0
	v_mov_b32_e32 v63, v0
	v_mov_b32_e32 v64, v0
	v_mov_b32_e32 v65, v0
	v_mov_b32_e32 v66, v0
	v_mov_b32_e32 v67, v0
	v_mov_b32_e32 v80, v0
	v_mov_b32_e32 v81, v0
	v_mov_b32_e32 v82, v0
	v_mov_b32_e32 v83, v0
	v_mov_b32_e32 v96, v0
	v_mov_b32_e32 v97, v0
	v_mov_b32_e32 v98, v0
	v_mov_b32_e32 v99, v0
	v_mov_b32_e32 v104, v0
	v_mov_b32_e32 v105, v0
	v_mov_b32_e32 v106, v0
	v_mov_b32_e32 v107, v0
	v_mov_b32_e32 v112, v0
	v_mov_b32_e32 v113, v0
	v_mov_b32_e32 v114, v0
	v_mov_b32_e32 v115, v0
	v_mov_b32_e32 v120, v0
	v_mov_b32_e32 v121, v0
	v_mov_b32_e32 v122, v0
	v_mov_b32_e32 v123, v0
	v_mov_b32_e32 v128, v0
	v_mov_b32_e32 v129, v0
	v_mov_b32_e32 v130, v0
	v_mov_b32_e32 v131, v0
	v_mov_b32_e32 v132, v0
	v_mov_b32_e32 v133, v0
	v_mov_b32_e32 v134, v0
	v_mov_b32_e32 v135, v0
	v_mov_b32_e32 v68, v0
	v_mov_b32_e32 v69, v0
	v_mov_b32_e32 v70, v0
	v_mov_b32_e32 v71, v0
	v_mov_b32_e32 v84, v0
	v_mov_b32_e32 v85, v0
	v_mov_b32_e32 v86, v0
	v_mov_b32_e32 v87, v0
	v_mov_b32_e32 v100, v0
	v_mov_b32_e32 v101, v0
	v_mov_b32_e32 v102, v0
	v_mov_b32_e32 v103, v0
	v_mov_b32_e32 v108, v0
	v_mov_b32_e32 v109, v0
	v_mov_b32_e32 v110, v0
	v_mov_b32_e32 v111, v0
	v_mov_b32_e32 v116, v0
	v_mov_b32_e32 v117, v0
	v_mov_b32_e32 v118, v0
	v_mov_b32_e32 v119, v0
	v_mov_b32_e32 v124, v0
	v_mov_b32_e32 v125, v0
	v_mov_b32_e32 v126, v0
	v_mov_b32_e32 v127, v0
	v_mov_b32_e32 v136, v0
	v_mov_b32_e32 v137, v0
	v_mov_b32_e32 v138, v0
	v_mov_b32_e32 v139, v0
	v_mov_b32_e32 v140, v0
	v_mov_b32_e32 v141, v0
	v_mov_b32_e32 v142, v0
	v_mov_b32_e32 v143, v0

.LBB0_615:
	s_add_u32 s20, s24, 0x100
	s_addc_u32 s85, s25, 0
	s_add_u32 s24, s46, 0x80
	v_mov_b32_e32 v0, 0
	s_addc_u32 s25, s47, 0
	s_mov_b32 s46, 0
	s_waitcnt lgkmcnt(0)
	v_mov_b32_e32 v1, v0
	v_mov_b32_e32 v2, v0
	v_mov_b32_e32 v3, v0
	v_mov_b32_e32 v4, v0
	v_mov_b32_e32 v5, v0
	v_mov_b32_e32 v6, v0
	v_mov_b32_e32 v7, v0
	v_mov_b32_e32 v16, v0
	v_mov_b32_e32 v17, v0
	v_mov_b32_e32 v18, v0
	v_mov_b32_e32 v19, v0
	v_mov_b32_e32 v20, v0
	v_mov_b32_e32 v21, v0
	v_mov_b32_e32 v22, v0
	v_mov_b32_e32 v23, v0
	v_mov_b32_e32 v32, v0
	v_mov_b32_e32 v33, v0
	v_mov_b32_e32 v34, v0
	v_mov_b32_e32 v35, v0
	v_mov_b32_e32 v36, v0
	v_mov_b32_e32 v37, v0
	v_mov_b32_e32 v38, v0
	v_mov_b32_e32 v39, v0
	v_mov_b32_e32 v64, v0
	v_mov_b32_e32 v65, v0
	v_mov_b32_e32 v66, v0
	v_mov_b32_e32 v67, v0
	v_mov_b32_e32 v68, v0
	v_mov_b32_e32 v69, v0
	v_mov_b32_e32 v70, v0
	v_mov_b32_e32 v71, v0
	v_mov_b32_e32 v8, v0
	v_mov_b32_e32 v9, v0
	v_mov_b32_e32 v10, v0
	v_mov_b32_e32 v11, v0
	v_mov_b32_e32 v12, v0
	v_mov_b32_e32 v13, v0
	v_mov_b32_e32 v14, v0
	v_mov_b32_e32 v15, v0
	v_mov_b32_e32 v24, v0
	v_mov_b32_e32 v25, v0
	v_mov_b32_e32 v26, v0
	v_mov_b32_e32 v27, v0
	v_mov_b32_e32 v28, v0
	v_mov_b32_e32 v29, v0
	v_mov_b32_e32 v30, v0
	v_mov_b32_e32 v31, v0
	v_mov_b32_e32 v48, v0
	v_mov_b32_e32 v49, v0
	v_mov_b32_e32 v50, v0
	v_mov_b32_e32 v51, v0
	v_mov_b32_e32 v56, v0
	v_mov_b32_e32 v57, v0
	v_mov_b32_e32 v58, v0
	v_mov_b32_e32 v59, v0
	v_mov_b32_e32 v72, v0
	v_mov_b32_e32 v73, v0
	v_mov_b32_e32 v74, v0
	v_mov_b32_e32 v75, v0
	v_mov_b32_e32 v76, v0
	v_mov_b32_e32 v77, v0
	v_mov_b32_e32 v78, v0
	v_mov_b32_e32 v79, v0
	v_mov_b32_e32 v80, v0
	v_mov_b32_e32 v81, v0
	v_mov_b32_e32 v82, v0
	v_mov_b32_e32 v83, v0
	v_mov_b32_e32 v84, v0
	v_mov_b32_e32 v85, v0
	v_mov_b32_e32 v86, v0
	v_mov_b32_e32 v87, v0
	v_mov_b32_e32 v96, v0
	v_mov_b32_e32 v97, v0
	v_mov_b32_e32 v98, v0
	v_mov_b32_e32 v99, v0
	v_mov_b32_e32 v100, v0
	v_mov_b32_e32 v101, v0
	v_mov_b32_e32 v102, v0
	v_mov_b32_e32 v103, v0
	v_mov_b32_e32 v112, v0
	v_mov_b32_e32 v113, v0
	v_mov_b32_e32 v114, v0
	v_mov_b32_e32 v115, v0
	v_mov_b32_e32 v116, v0
	v_mov_b32_e32 v117, v0
	v_mov_b32_e32 v118, v0
	v_mov_b32_e32 v119, v0
	v_mov_b32_e32 v128, v0
	v_mov_b32_e32 v129, v0
	v_mov_b32_e32 v130, v0
	v_mov_b32_e32 v131, v0
	v_mov_b32_e32 v132, v0
	v_mov_b32_e32 v133, v0
	v_mov_b32_e32 v134, v0
	v_mov_b32_e32 v135, v0
	v_mov_b32_e32 v88, v0
	v_mov_b32_e32 v89, v0
	v_mov_b32_e32 v90, v0
	v_mov_b32_e32 v91, v0
	v_mov_b32_e32 v92, v0
	v_mov_b32_e32 v93, v0
	v_mov_b32_e32 v94, v0
	v_mov_b32_e32 v95, v0
	v_mov_b32_e32 v104, v0
	v_mov_b32_e32 v105, v0
	v_mov_b32_e32 v106, v0
	v_mov_b32_e32 v107, v0
	v_mov_b32_e32 v108, v0
	v_mov_b32_e32 v109, v0
	v_mov_b32_e32 v110, v0
	v_mov_b32_e32 v111, v0
	v_mov_b32_e32 v120, v0
	v_mov_b32_e32 v121, v0
	v_mov_b32_e32 v122, v0
	v_mov_b32_e32 v123, v0
	v_mov_b32_e32 v124, v0
	v_mov_b32_e32 v125, v0
	v_mov_b32_e32 v126, v0
	v_mov_b32_e32 v127, v0
	v_mov_b32_e32 v136, v0
	v_mov_b32_e32 v137, v0
	v_mov_b32_e32 v138, v0
	v_mov_b32_e32 v139, v0
	v_mov_b32_e32 v140, v0
	v_mov_b32_e32 v141, v0
	v_mov_b32_e32 v142, v0
	v_mov_b32_e32 v143, v0
